# GDN output-norm phase: next row's loads issued before this row's stores (software-pipelined, counted vmcnt), no store-ack wait per row
# speedup vs baseline: 1.0095x; 1.0095x over previous
; DI float bflo(unsigned u) { return __uint_as_float(u << 16); }
; DI float bfhi(unsigned u) { return __uint_as_float(u & 0xffff0000u); }
; DI int fresh_tid(const Params& p) { int t = p.wave_u * 64 + (int)__builtin_amdgcn_mbcnt_hi(~0u, __builtin_amdgcn_mbcnt_lo(~0u, 0u)); asm volatile("" : "+v"(t)); return t; }
; DI void phase_norm(const Params& p) {
;     const int tid = fresh_tid(p), lane = tid & 63, wave = tid >> 6;
;     const bf16_t* pa = (const bf16_t*)(p.ws + WS_PA); bf16_t* mixed = (bf16_t*)(p.ws + WS_MIXED);
;     const int col = lane * 16;
;     f32x4 gn[4];
; #pragma unroll
;     for (int i = 0; i < 4; ++i) gn[i] = *(const f32x4*)(p.out_gain + (col & 127) + 4 * i);
;     for (int row = p.vb * 4 + wave; row < T_; row += p.vg * 4) {
;         bf16_t* mp = mixed + (size_t)row * LDK + 1024 + col;
;         const bf16_t* gp = pa + (size_t)row * LDPA + C_GG + col;
;         const u32x4 a0 = *(const u32x4*)mp, a1 = *(const u32x4*)(mp + 8);
;         const u32x4 g0 = *(const u32x4*)gp, g1 = *(const u32x4*)(gp + 8);
;         float v[16] = {bflo(a0.x), bfhi(a0.x), bflo(a0.y), bfhi(a0.y), bflo(a0.z), bfhi(a0.z), bflo(a0.w), bfhi(a0.w),
;                        bflo(a1.x), bfhi(a1.x), bflo(a1.y), bfhi(a1.y), bflo(a1.z), bfhi(a1.z), bflo(a1.w), bfhi(a1.w)};
;         const float gt[16] = {bflo(g0.x), bfhi(g0.x), bflo(g0.y), bfhi(g0.y), bflo(g0.z), bfhi(g0.z), bflo(g0.w), bfhi(g0.w),
;                               bflo(g1.x), bfhi(g1.x), bflo(g1.y), bfhi(g1.y), bflo(g1.z), bfhi(g1.z), bflo(g1.w), bfhi(g1.w)};
;         float ss = 0.f;
; #pragma unroll
;         for (int i = 0; i < 16; ++i) ss += v[i] * v[i];
;         ss += __shfl_xor(ss, 1); ss += __shfl_xor(ss, 2); ss += __shfl_xor(ss, 4);
.LBB0_481:
	v_mov_b32_e32 v16, v227
	s_barrier
	v_readlane_b32 s4, v246, 0
	v_ashrrev_i32_e32 v0, 6, v16
	s_nop 0
	v_add_u32_e32 v38, s4, v0
	s_mov_b32 s4, 0x8000
	v_cmp_gt_i32_e32 vcc, s4, v38
	s_and_saveexec_b64 s[36:37], vcc
	s_cbranch_execz .LBB0_484
	v_lshlrev_b32_e32 v0, 6, v16
	v_and_b32_e32 v17, 0x1c0, v0
	global_load_dwordx4 v[0:3], v17, s[66:67] offset:48
	global_load_dwordx4 v[4:7], v17, s[66:67] offset:32
	global_load_dwordx4 v[8:11], v17, s[66:67] offset:16
	global_load_dwordx4 v[12:15], v17, s[66:67]
	v_cmp_lt_i32_e32 vcc, v239, v240
	v_and_b32_e32 v16, 63, v16
	v_lshlrev_b32_e32 v18, 5, v16
	v_cndmask_b32_e32 v17, v236, v239, vcc
	v_cmp_lt_i32_e32 vcc, v238, v240
	v_lshlrev_b32_e32 v39, 2, v17
	v_mov_b32_e32 v19, 0
	v_cndmask_b32_e32 v17, v236, v238, vcc
	v_cmp_lt_i32_e32 vcc, v237, v240
	v_lshlrev_b32_e32 v40, 2, v17
	s_movk_i32 s4, 0x1700
	v_cndmask_b32_e32 v17, v236, v237, vcc
	v_lshlrev_b32_e32 v41, 2, v17
	v_mad_i64_i32 v[16:17], s[4:5], v38, s4, v[18:19]
	s_lshl_b32 s56, s33, 3
	s_movk_i32 s4, 0x1080
	s_mul_i32 s44, s33, 0xb800
	s_mul_hi_i32 s45, s56, 0x1700
	s_mul_i32 s46, s33, 0x8400
	s_mul_hi_i32 s47, s56, 0x1080
	v_mad_i64_i32 v[18:19], s[4:5], v38, s4, v[18:19]
	s_mov_b64 s[48:49], 0
	s_mov_b64 s[50:51], 0xddc5800
	s_mov_b64 s[52:53], 0x25c5f00
	s_mov_b32 s57, 0x25c5000
	v_mov_b32_e32 v42, 0x358637bd
	s_mov_b32 s58, 0x800000
	s_movk_i32 s59, 0x7fff
	s_add_u32 s100, s72, 0xddc5000
	s_addc_u32 s101, s73, 0
	s_add_u32 s98, s72, 0x25c5000
	s_addc_u32 s99, s73, 0
	v_lshl_add_u64 v[176:177], v[18:19], 0, s[100:101]
	v_lshl_add_u64 v[178:179], v[16:17], 0, s[98:99]
	global_load_dwordx4 v[160:163], v[176:177], off offset:2064
	global_load_dwordx4 v[164:167], v[178:179], off offset:3856
	global_load_dwordx4 v[168:171], v[176:177], off offset:2048
	global_load_dwordx4 v[172:175], v[178:179], off offset:3840
	v_lshl_add_u64 v[16:17], v[16:17], 0, s[44:45]
	v_lshl_add_u64 v[18:19], v[18:19], 0, s[46:47]
	s_waitcnt vmcnt(0)
.LBB0_483:
	v_mov_b32_e32 v22, v176
	v_mov_b32_e32 v23, v177
	v_add_u32_e32 v38, s56, v38
	v_cmp_lt_i32_e64 s[4:5], s59, v38
	s_or_b64 s[48:49], s[4:5], s[48:49]
	s_waitcnt vmcnt(2)
	v_lshlrev_b32_e32 v20, 16, v163
	v_lshlrev_b32_e32 v75, 16, v166
	v_and_b32_e32 v76, 0xffff0000, v166
	v_lshlrev_b32_e32 v43, 16, v167
	v_and_b32_e32 v74, 0xffff0000, v167
	v_lshlrev_b32_e32 v79, 16, v164
	v_and_b32_e32 v80, 0xffff0000, v164
	v_mul_f32_e32 v60, 0xbfb8aa3b, v75
	v_mul_f32_e32 v61, 0xbfb8aa3b, v76
	v_lshlrev_b32_e32 v36, 16, v168
	v_and_b32_e32 v37, 0xffff0000, v168
	v_lshlrev_b32_e32 v77, 16, v165
	v_and_b32_e32 v78, 0xffff0000, v165
	v_mul_f32_e32 v64, 0xbfb8aa3b, v79
	v_mul_f32_e32 v65, 0xbfb8aa3b, v80
	v_lshlrev_b32_e32 v34, 16, v169
	v_and_b32_e32 v35, 0xffff0000, v169
	v_exp_f32_e32 v44, v60
	v_exp_f32_e32 v45, v61
	v_lshlrev_b32_e32 v85, 16, v173
	v_and_b32_e32 v86, 0xffff0000, v173
	v_lshlrev_b32_e32 v87, 16, v172
	v_and_b32_e32 v88, 0xffff0000, v172
	v_pk_mul_f32 v[48:49], v[36:37], v[36:37]
	v_mul_f32_e32 v62, 0xbfb8aa3b, v77
	v_mul_f32_e32 v63, 0xbfb8aa3b, v78
	v_mul_f32_e32 v66, 0xbfb8aa3b, v43
	v_mul_f32_e32 v67, 0xbfb8aa3b, v74
	v_exp_f32_e32 v60, v64
	v_exp_f32_e32 v61, v65
	v_pk_mul_f32 v[64:65], v[34:35], v[34:35]
	v_add_f32_e32 v91, v48, v49
	v_and_b32_e32 v21, 0xffff0000, v163
	v_lshlrev_b32_e32 v24, 16, v162
	v_and_b32_e32 v25, 0xffff0000, v162
	v_lshlrev_b32_e32 v26, 16, v161
	v_and_b32_e32 v27, 0xffff0000, v161
	v_lshlrev_b32_e32 v28, 16, v160
	v_and_b32_e32 v29, 0xffff0000, v160
	v_lshlrev_b32_e32 v30, 16, v171
	v_and_b32_e32 v31, 0xffff0000, v171
	v_lshlrev_b32_e32 v32, 16, v170
	v_and_b32_e32 v33, 0xffff0000, v170
	v_exp_f32_e32 v46, v62
	v_exp_f32_e32 v47, v63
	v_lshlrev_b32_e32 v81, 16, v175
	v_and_b32_e32 v82, 0xffff0000, v175
	v_lshlrev_b32_e32 v83, 16, v174
	v_and_b32_e32 v84, 0xffff0000, v174
	v_lshl_add_u64 v[176:177], v[18:19], 0, s[100:101]
	v_lshl_add_u64 v[178:179], v[16:17], 0, s[98:99]
	global_load_dwordx4 v[160:163], v[176:177], off offset:2064
	global_load_dwordx4 v[164:167], v[178:179], off offset:3856
	global_load_dwordx4 v[168:171], v[176:177], off offset:2048
	global_load_dwordx4 v[172:175], v[178:179], off offset:3840
	v_lshl_add_u64 v[16:17], v[16:17], 0, s[44:45]
	v_lshl_add_u64 v[18:19], v[18:19], 0, s[46:47]
	v_exp_f32_e32 v66, v66
	v_exp_f32_e32 v67, v67
	v_add_f32_e32 v64, v64, v91
	v_pk_mul_f32 v[50:51], v[32:33], v[32:33]
	v_mul_f32_e32 v68, 0xbfb8aa3b, v81
	v_mul_f32_e32 v69, 0xbfb8aa3b, v82
	v_mul_f32_e32 v70, 0xbfb8aa3b, v83
	v_mul_f32_e32 v71, 0xbfb8aa3b, v84
	v_mul_f32_e32 v72, 0xbfb8aa3b, v85
	v_mul_f32_e32 v73, 0xbfb8aa3b, v86
	v_add_f32_e32 v64, v65, v64
	v_mul_f32_e32 v89, 0xbfb8aa3b, v87
	v_exp_f32_e32 v48, v68
	v_exp_f32_e32 v49, v69
	v_exp_f32_e32 v68, v70
	v_exp_f32_e32 v69, v71
	v_exp_f32_e32 v70, v72
	v_exp_f32_e32 v71, v73
	v_pk_add_f32 v[44:45], v[44:45], 1.0 op_sel_hi:[1,0]
	v_add_f32_e32 v50, v50, v64
	v_pk_mul_f32 v[62:63], v[30:31], v[30:31]
	v_exp_f32_e32 v72, v89
	v_div_scale_f32 v89, s[4:5], v45, v45, v76
	v_add_f32_e32 v101, v51, v50
	v_mul_f32_e32 v90, 0xbfb8aa3b, v88
	v_pk_add_f32 v[46:47], v[46:47], 1.0 op_sel_hi:[1,0]
	v_pk_add_f32 v[64:65], v[66:67], 1.0 op_sel_hi:[1,0]
	v_div_scale_f32 v91, s[4:5], v44, v44, v75
	v_rcp_f32_e32 v106, v89
	v_add_f32_e32 v62, v62, v101
	v_pk_mul_f32 v[58:59], v[28:29], v[28:29]
	v_exp_f32_e32 v73, v90
	v_div_scale_f32 v93, s[4:5], v47, v47, v78
	v_div_scale_f32 v102, s[4:5], v65, v65, v74
	v_rcp_f32_e32 v107, v91
	v_add_f32_e32 v62, v63, v62
	v_pk_add_f32 v[60:61], v[60:61], 1.0 op_sel_hi:[1,0]
	v_div_scale_f32 v95, s[4:5], v46, v46, v77
	v_rcp_f32_e32 v108, v93
	v_pk_add_f32 v[66:67], v[70:71], 1.0 op_sel_hi:[1,0]
; DI float silu_f(float y) { return y / (1.f + __expf(-y)); }
; DI void phase_norm(const Params& p) {
;     ...
;         for (int i = 0; i < 16; ++i) ss += v[i] * v[i];
;         ss += __shfl_xor(ss, 1); ss += __shfl_xor(ss, 2); ss += __shfl_xor(ss, 4);
;         const float rs = rsqrtf(ss * (1.f / 128.f) + EPS);
; #pragma unroll
;         for (int i = 0; i < 16; ++i) v[i] = v[i] * rs * gn[i >> 2][i & 3] * silu_f(gt[i]);
	v_rcp_f32_e32 v70, v102
	v_add_f32_e32 v58, v58, v62
	v_pk_mul_f32 v[56:57], v[26:27], v[26:27]
	v_div_scale_f32 v97, s[4:5], v61, v61, v80
	v_rcp_f32_e32 v109, v95
	v_add_f32_e32 v58, v59, v58
	v_div_scale_f32 v99, s[4:5], v60, v60, v79
	v_rcp_f32_e32 v110, v97
	v_pk_add_f32 v[48:49], v[48:49], 1.0 op_sel_hi:[1,0]
	v_fma_f32 v59, -v89, v106, 1.0
	v_add_f32_e32 v56, v56, v58
	v_pk_mul_f32 v[54:55], v[24:25], v[24:25]
	v_div_scale_f32 v90, vcc, v76, v45, v76
	v_rcp_f32_e32 v111, v99
	v_pk_add_f32 v[50:51], v[68:69], 1.0 op_sel_hi:[1,0]
	v_pk_add_f32 v[68:69], v[72:73], 1.0 op_sel_hi:[1,0]
	v_div_scale_f32 v72, s[16:17], v49, v49, v82
	v_fma_f32 v62, -v91, v107, 1.0
	v_fmac_f32_e32 v106, v59, v106
	v_add_f32_e32 v56, v57, v56
	v_div_scale_f32 v92, s[24:25], v75, v44, v75
	v_rcp_f32_e32 v63, v72
	v_fma_f32 v132, -v93, v108, 1.0
	v_fma_f32 v58, -v102, v70, 1.0
	v_fmac_f32_e32 v107, v62, v107
	v_mul_f32_e32 v57, v90, v106
	v_add_f32_e32 v54, v54, v56
	v_pk_mul_f32 v[52:53], v[20:21], v[20:21]
	v_div_scale_f32 v94, s[14:15], v78, v47, v78
	v_div_scale_f32 v103, s[6:7], v74, v65, v74
	v_div_scale_f32 v104, s[4:5], v64, v64, v43
	v_div_scale_f32 v101, s[16:17], v48, v48, v81
	v_fma_f32 v133, -v95, v109, 1.0
	v_fmac_f32_e32 v108, v132, v108
	v_fmac_f32_e32 v70, v58, v70
	v_mul_f32_e32 v58, v92, v107
	v_fma_f32 v56, -v89, v57, v90
	v_add_f32_e32 v54, v55, v54
	v_div_scale_f32 v96, s[12:13], v77, v46, v77
	v_rcp_f32_e32 v71, v104
	v_div_scale_f32 v113, s[16:17], v51, v51, v84
	v_rcp_f32_e32 v125, v101
	v_fma_f32 v134, -v97, v110, 1.0
	v_fmac_f32_e32 v109, v133, v109
	v_mul_f32_e32 v59, v94, v108
	v_mul_f32_e32 v142, v103, v70
	v_fma_f32 v144, -v91, v58, v92
	v_fmac_f32_e32 v57, v56, v106
	v_add_f32_e32 v52, v52, v54
	v_div_scale_f32 v98, s[10:11], v80, v61, v80
	v_div_scale_f32 v115, s[16:17], v50, v50, v83
	v_rcp_f32_e32 v126, v113
	v_fma_f32 v135, -v99, v111, 1.0
	v_fmac_f32_e32 v110, v134, v110
	v_mul_f32_e32 v62, v96, v109
	v_fma_f32 v145, -v93, v59, v94
	v_fma_f32 v55, -v102, v142, v103
	v_fmac_f32_e32 v58, v144, v107
	v_fma_f32 v54, -v89, v57, v90
	v_add_f32_e32 v52, v53, v52
	v_div_scale_f32 v100, s[8:9], v79, v60, v79
	v_div_scale_f32 v117, s[16:17], v67, v67, v86
	v_rcp_f32_e32 v127, v115
	v_fmac_f32_e32 v111, v135, v111
	v_mul_f32_e32 v132, v98, v110
	v_fma_f32 v134, -v72, v63, 1.0
	v_fma_f32 v146, -v95, v62, v96
	v_fmac_f32_e32 v59, v145, v108
	v_fmac_f32_e32 v142, v55, v70
	v_fma_f32 v55, -v91, v58, v92
	v_div_fmas_f32 v53, v54, v106, v57
	ds_bpermute_b32 v54, v39, v52
	s_mov_b64 vcc, s[24:25]
	v_div_scale_f32 v73, s[34:35], v82, v49, v82
	v_div_scale_f32 v119, s[16:17], v66, v66, v85
	v_rcp_f32_e32 v128, v117
	v_mul_f32_e32 v133, v100, v111
	v_fma_f32 v147, -v97, v132, v98
	v_fmac_f32_e32 v63, v134, v63
	v_fmac_f32_e32 v62, v146, v109
	v_fma_f32 v89, -v93, v59, v94
	v_div_fixup_f32 v45, v53, v45, v76
	v_div_fmas_f32 v53, v55, v107, v58
	s_mov_b64 vcc, s[14:15]
	v_div_scale_f32 v121, s[16:17], v69, v69, v88
	v_rcp_f32_e32 v129, v119
	v_fma_f32 v136, -v104, v71, 1.0
	v_fma_f32 v135, -v101, v125, 1.0
	v_fma_f32 v148, -v99, v133, v100
	v_fmac_f32_e32 v132, v147, v110
	v_mul_f32_e32 v56, v73, v63
	v_fma_f32 v90, -v95, v62, v96
	v_div_fixup_f32 v44, v53, v44, v75
	v_div_fmas_f32 v53, v89, v108, v59
	s_mov_b64 vcc, s[12:13]
	v_div_scale_f32 v112, s[30:31], v81, v48, v81
	v_div_scale_f32 v123, s[16:17], v68, v68, v87
	v_rcp_f32_e32 v130, v121
	v_fmac_f32_e32 v71, v136, v71
	v_fma_f32 v136, -v113, v126, 1.0
	v_fmac_f32_e32 v125, v135, v125
	v_fmac_f32_e32 v133, v148, v111
	v_fma_f32 v91, -v97, v132, v98
	v_fma_f32 v93, -v72, v56, v73
	v_div_fixup_f32 v47, v53, v47, v78
	v_div_fmas_f32 v53, v90, v109, v62
	s_mov_b64 vcc, s[10:11]
	v_div_scale_f32 v114, s[28:29], v84, v51, v84
	v_rcp_f32_e32 v131, v123
	v_fma_f32 v137, -v115, v127, 1.0
	v_fmac_f32_e32 v126, v136, v126
	v_mul_f32_e32 v135, v112, v125
	v_fma_f32 v92, -v99, v133, v100
	v_fmac_f32_e32 v56, v93, v63
	v_div_fixup_f32 v46, v53, v46, v77
	v_div_fmas_f32 v53, v91, v110, v132
	s_mov_b64 vcc, s[8:9]
	v_div_scale_f32 v116, s[26:27], v83, v50, v83
	v_fma_f32 v138, -v117, v128, 1.0
	v_fmac_f32_e32 v127, v137, v127
	v_mul_f32_e32 v136, v114, v126
	v_fma_f32 v94, -v101, v135, v112
	v_fma_f32 v55, -v72, v56, v73
	v_div_fmas_f32 v59, v92, v111, v133
	s_waitcnt lgkmcnt(0)
; DI unsigned pk2(float a, float b) { f2_t v = {a, b}; bf2_t r = __builtin_convertvector(v, bf2_t); return __builtin_bit_cast(unsigned, r); }
; DI float silu_f(float y) { return y / (1.f + __expf(-y)); }
; DI void phase_norm(const Params& p) {
;     ...
;         ss += __shfl_xor(ss, 1); ss += __shfl_xor(ss, 2); ss += __shfl_xor(ss, 4);
;         const float rs = rsqrtf(ss * (1.f / 128.f) + EPS);
; #pragma unroll
;         for (int i = 0; i < 16; ++i) v[i] = v[i] * rs * gn[i >> 2][i & 3] * silu_f(gt[i]);
;         u32x4 o0, o1;
;         o0.x = pk2(v[0], v[1]); o0.y = pk2(v[2], v[3]); o0.z = pk2(v[4], v[5]); o0.w = pk2(v[6], v[7]);
;         o1.x = pk2(v[8], v[9]); o1.y = pk2(v[10], v[11]); o1.z = pk2(v[12], v[13]); o1.w = pk2(v[14], v[15]);
;         *(u32x4*)mp = o0; *(u32x4*)(mp + 8) = o1;
	v_add_f32_e32 v54, v52, v54
	s_mov_b64 vcc, s[34:35]
	v_div_scale_f32 v118, s[22:23], v86, v67, v86
	v_fma_f32 v139, -v119, v129, 1.0
	v_fmac_f32_e32 v128, v138, v128
	v_mul_f32_e32 v137, v116, v127
	v_fma_f32 v95, -v113, v136, v114
	v_fmac_f32_e32 v135, v94, v125
	v_div_fmas_f32 v55, v55, v63, v56
	ds_bpermute_b32 v56, v40, v54
	v_div_scale_f32 v120, s[20:21], v85, v66, v85
	v_fma_f32 v140, -v121, v130, 1.0
	v_fmac_f32_e32 v129, v139, v129
	v_mul_f32_e32 v138, v118, v128
	v_fma_f32 v96, -v115, v137, v116
	v_fmac_f32_e32 v136, v95, v126
	v_fma_f32 v57, -v101, v135, v112
	s_mov_b64 vcc, s[30:31]
	v_div_scale_f32 v122, s[18:19], v88, v69, v88
	v_fma_f32 v141, -v123, v131, 1.0
	v_fmac_f32_e32 v130, v140, v130
	v_mul_f32_e32 v139, v120, v129
	v_fma_f32 v97, -v117, v138, v118
	v_fmac_f32_e32 v137, v96, v127
	v_fma_f32 v58, -v113, v136, v114
	v_div_fixup_f32 v49, v55, v49, v82
	v_div_fmas_f32 v55, v57, v125, v135
	s_mov_b64 vcc, s[28:29]
	v_div_scale_f32 v124, s[16:17], v87, v68, v87
	v_fmac_f32_e32 v131, v141, v131
	v_mul_f32_e32 v140, v122, v130
	v_fma_f32 v98, -v119, v139, v120
	v_fmac_f32_e32 v138, v97, v128
	v_fma_f32 v72, -v115, v137, v116
	v_div_fixup_f32 v48, v55, v48, v81
	v_div_fmas_f32 v55, v58, v126, v136
	s_mov_b64 vcc, s[26:27]
	v_mul_f32_e32 v141, v124, v131
	v_fma_f32 v99, -v121, v140, v122
	v_fmac_f32_e32 v139, v98, v129
	v_fma_f32 v73, -v117, v138, v118
	v_div_fixup_f32 v51, v55, v51, v84
	v_div_fmas_f32 v55, v72, v127, v137
	s_mov_b64 vcc, s[22:23]
	v_div_scale_f32 v105, s[4:5], v43, v64, v43
	v_fma_f32 v100, -v123, v141, v124
	v_fmac_f32_e32 v140, v99, v130
	v_fma_f32 v76, -v119, v139, v120
	v_div_fixup_f32 v52, v59, v60, v79
	v_div_fixup_f32 v50, v55, v50, v83
	v_div_fmas_f32 v55, v73, v128, v138
	s_mov_b64 vcc, s[20:21]
	s_waitcnt lgkmcnt(0)
	v_add_f32_e32 v60, v54, v56
	v_mul_f32_e32 v143, v105, v71
	v_fmac_f32_e32 v141, v100, v131
	v_fma_f32 v93, -v121, v140, v122
	v_div_fixup_f32 v53, v53, v61, v80
	v_div_fmas_f32 v57, v76, v129, v139
	s_mov_b64 vcc, s[18:19]
	ds_bpermute_b32 v61, v41, v60
	v_fma_f32 v134, -v104, v143, v105
	v_fma_f32 v94, -v123, v141, v124
	v_div_fmas_f32 v56, v93, v130, v140
	s_mov_b64 vcc, s[16:17]
	v_fmac_f32_e32 v143, v134, v71
	v_fma_f32 v102, -v102, v142, v103
	v_div_fixup_f32 v54, v57, v66, v85
	v_div_fixup_f32 v57, v56, v69, v88
	v_div_fmas_f32 v56, v94, v131, v141
	s_mov_b64 vcc, s[6:7]
	v_fma_f32 v103, -v104, v143, v105
	v_div_fmas_f32 v58, v102, v70, v142
	s_mov_b64 vcc, s[4:5]
	v_div_fixup_f32 v59, v58, v65, v74
	v_div_fmas_f32 v58, v103, v71, v143
	v_div_fixup_f32 v58, v58, v64, v43
	s_waitcnt lgkmcnt(0)
	v_add_f32_e32 v43, v60, v61
	v_fmamk_f32 v43, v43, 0x3c000000, v42
	v_mul_f32_e32 v60, 0x4b800000, v43
	v_cmp_gt_f32_e32 vcc, s58, v43
	v_div_fixup_f32 v55, v55, v67, v86
	v_div_fixup_f32 v56, v56, v68, v87
	v_cndmask_b32_e32 v43, v43, v60, vcc
	v_rsq_f32_e32 v43, v43
	s_nop 0
	v_mul_f32_e32 v60, 0x45800000, v43
	v_cndmask_b32_e32 v60, v43, v60, vcc
	v_pk_mul_f32 v[36:37], v[60:61], v[36:37] op_sel_hi:[0,1]
	v_pk_mul_f32 v[34:35], v[60:61], v[34:35] op_sel_hi:[0,1]
	v_pk_mul_f32 v[32:33], v[60:61], v[32:33] op_sel_hi:[0,1]
	v_pk_mul_f32 v[30:31], v[60:61], v[30:31] op_sel_hi:[0,1]
	v_pk_mul_f32 v[28:29], v[60:61], v[28:29] op_sel_hi:[0,1]
	v_pk_mul_f32 v[26:27], v[60:61], v[26:27] op_sel_hi:[0,1]
	v_pk_mul_f32 v[24:25], v[60:61], v[24:25] op_sel_hi:[0,1]
	v_pk_mul_f32 v[20:21], v[60:61], v[20:21] op_sel_hi:[0,1]
	v_pk_mul_f32 v[36:37], v[12:13], v[36:37]
	v_pk_mul_f32 v[34:35], v[14:15], v[34:35]
	v_pk_mul_f32 v[32:33], v[8:9], v[32:33]
	v_pk_mul_f32 v[30:31], v[10:11], v[30:31]
	v_pk_mul_f32 v[28:29], v[4:5], v[28:29]
	v_pk_mul_f32 v[26:27], v[6:7], v[26:27]
	v_pk_mul_f32 v[24:25], v[0:1], v[24:25]
	v_pk_mul_f32 v[20:21], v[2:3], v[20:21]
	v_pk_mul_f32 v[36:37], v[56:57], v[36:37]
	v_pk_mul_f32 v[34:35], v[54:55], v[34:35]
	v_pk_mul_f32 v[32:33], v[50:51], v[32:33]
	v_pk_mul_f32 v[30:31], v[48:49], v[30:31]
	v_pk_mul_f32 v[28:29], v[52:53], v[28:29]
	v_pk_mul_f32 v[46:47], v[46:47], v[26:27]
	v_pk_mul_f32 v[44:45], v[44:45], v[24:25]
	v_pk_mul_f32 v[20:21], v[58:59], v[20:21]
	v_cvt_pk_bf16_f32 v24, v36, v37
	v_cvt_pk_bf16_f32 v25, v34, v35
	v_cvt_pk_bf16_f32 v26, v32, v33
	v_cvt_pk_bf16_f32 v27, v30, v31
	v_cvt_pk_bf16_f32 v28, v28, v29
	v_cvt_pk_bf16_f32 v29, v46, v47
	v_cvt_pk_bf16_f32 v30, v44, v45
	v_cvt_pk_bf16_f32 v31, v20, v21
	global_store_dwordx4 v[22:23], v[24:27], off offset:2048
	global_store_dwordx4 v[22:23], v[28:31], off offset:2064
	s_andn2_b64 exec, exec, s[48:49]
	s_cbranch_execnz .LBB0_483
